# rw_phaseA forward substitution moved to the f32 matrix cores (v_mfma_f32_16x16x4_f32, blocked 16x16, all 8 waves); f32 operands and accumulation as before
# speedup vs baseline: 1.0491x; 1.0122x over previous
; #define LAS __attribute__((address_space(3)))
; __device__ __forceinline__ unsigned cvt_pk_bf16(float lo, float hi) { const bf16x2_t r = __builtin_convertvector((f32x2){lo, hi}, bf16x2_t); return __builtin_bit_cast(unsigned, r); }
; #define LDS_BAR() do { asm volatile("s_waitcnt lgkmcnt(0)" ::: "memory"); __builtin_amdgcn_s_barrier(); asm volatile("" ::: "memory"); } while (0)
; __device__ __forceinline__ void rw_phaseA(LAS unsigned char* lds, const RwCtx& X, int item) {
;     ...
; #pragma unroll
;             for (int j = 0; j < 4; ++j) { const int tt = t0b + fq * 4 + j, sidx = s0 + fr; LAB[tt * 68 + sidx] = (sidx < tt) ? acc[j] : 0.f; }
;             float p[4];
; #pragma unroll
;             for (int j = 0; j < 4; ++j) p[j] = (s0 + fq * 4 + j < t0b + fr) ? acc2[j] : 0.f;
;             u32x2 o; o.x = cvt_pk_bf16(p[0], p[1]); o.y = cvt_pk_bf16(p[2], p[3]);
;             *(LAS u32x2*)(LAK + (t0b + fr) * 72 + s0 + fq * 4) = o; }
;     }
;     LDS_BAR();
;     {
;         bf16x8 fl[2];
; #pragma unroll
;         for (int k = 0; k < 2; ++k) fl[k] = *(const LAS bf16x8*)(LAK + (t0b + fr) * 72 + k * 32 + fq * 8);
; #pragma unroll
;         for (int bi = 0; bi < 2; ++bi) { const int v0 = ((wave & 1) * 2 + bi) * 16; f32x4 acc = (f32x4){0.f, 0.f, 0.f, 0.f};
; #pragma unroll
;             for (int k = 0; k < 2; ++k) { const bf16x8 fv = *(const LAS bf16x8*)(VT + (v0 + fr) * 72 + k * 32 + fq * 8); acc = __builtin_amdgcn_mfma_f32_16x16x32_bf16(fl[k], fv, acc, 0, 0, 0); }
; #pragma unroll
;             for (int j = 0; j < 4; ++j) XS[(t0b + fq * 4 + j) * 129 + 64 + v0 + fr] = acc[j]; }
;     }
;     LDS_BAR();
;     int tid_s = threadIdx.x; asm volatile("" : "+v"(tid_s));
;     if (tid_s < 128) {
;         float x[64];
;         int zv = 0; asm volatile("" : "+v"(zv));
;         const LAS float* LABv = LAB + zv;
; #pragma unroll
;         for (int i = 0; i < 64; ++i) x[i] = XS[i * 129 + tid_s];
; #pragma unroll
;         for (int tt = 1; tt < 64; ++tt) { float a = x[tt];
; #pragma unroll
;             for (int s4 = 0; s4 < (tt + 3) / 4; ++s4) { const f32x4 l4 = *(const LAS f32x4*)(LABv + tt * 68 + s4 * 4);
;                 a += l4[0] * x[s4 * 4]; if (s4 * 4 + 1 < tt) a += l4[1] * x[s4 * 4 + 1]; if (s4 * 4 + 2 < tt) a += l4[2] * x[s4 * 4 + 2]; if (s4 * 4 + 3 < tt) a += l4[3] * x[s4 * 4 + 3]; }
;             x[tt] = a;
.LBB0_801:
	s_or_b64 exec, exec, s[0:1]
	v_cmp_lt_i32_e32 vcc, v18, v27
	s_waitcnt lgkmcnt(5)
	v_lshlrev_b32_e32 v5, 2, v18
	v_add3_u32 v6, s88, v30, v5
	v_cndmask_b32_e32 v4, 0, v14, vcc
	v_cmp_le_i32_e32 vcc, v18, v27
	ds_write_b32 v6, v4
	v_add3_u32 v6, s88, v19, v5
	v_cndmask_b32_e32 v4, 0, v15, vcc
	v_cmp_lt_i32_e32 vcc, v18, v31
	ds_write_b32 v6, v4
	v_add3_u32 v6, s88, v20, v5
	v_cndmask_b32_e32 v4, 0, v16, vcc
	v_cmp_lt_i32_e32 vcc, v18, v32
	ds_write_b32 v6, v4
	v_add3_u32 v5, s88, v21, v5
	v_cndmask_b32_e32 v4, 0, v17, vcc
	ds_write_b32 v5, v4
	v_or_b32_e32 v4, v34, v29
	v_cmp_lt_i32_e32 vcc, v4, v26
	v_or_b32_e32 v5, 1, v4
	v_mad_u32_u24 v14, v25, s91, v22
	v_cndmask_b32_e32 v0, 0, v0, vcc
	v_cmp_lt_i32_e32 vcc, v5, v26
	v_or_b32_e32 v5, 2, v4
	v_or_b32_e32 v4, 3, v4
	v_cndmask_b32_e32 v1, 0, v1, vcc
	v_cmp_lt_i32_e32 vcc, v5, v26
	v_cvt_pk_bf16_f32 v0, v0, v1
	s_movk_i32 s0, 0x204
	v_cndmask_b32_e32 v2, 0, v2, vcc
	v_cmp_lt_i32_e32 vcc, v4, v26
	v_add_u32_e32 v4, v28, v24
	v_lshlrev_b32_e32 v8, 2, v8
	v_cndmask_b32_e32 v3, 0, v3, vcc
	v_cvt_pk_bf16_f32 v1, v2, v3
	ds_write_b64 v33, v[0:1] offset:32
	s_waitcnt lgkmcnt(0)
	s_barrier
	ds_read_b128 v[0:3], v4
	ds_read_b128 v[4:7], v4 offset:64
	ds_read_b128 v[10:13], v14 offset:46080
	ds_read_b128 v[14:17], v14 offset:46144
	s_waitcnt lgkmcnt(1)
	v_mfma_f32_16x16x32_bf16 v[10:13], v[0:3], v[10:13], 0
	v_mov_b32_e32 v247, v226
	s_waitcnt lgkmcnt(0)
	v_mfma_f32_16x16x32_bf16 v[10:13], v[4:7], v[14:17], v[10:13]
	v_mul_lo_u32 v14, v27, s0
	v_add_u32_e32 v14, 0, v14
	v_lshlrev_b32_e32 v15, 2, v23
	v_add3_u32 v8, v14, v15, v8
	s_nop 3
	ds_write_b32 v8, v10 offset:55552
	ds_write_b32 v8, v11 offset:56068
	ds_write_b32 v8, v12 offset:56584
	ds_write_b32 v8, v13 offset:57100
	v_mad_u32_u24 v14, v18, s91, v22
	ds_read_b128 v[10:13], v14 offset:46080
	ds_read_b128 v[14:17], v14 offset:46144
	s_waitcnt lgkmcnt(1)
	v_mfma_f32_16x16x32_bf16 v[0:3], v[0:3], v[10:13], 0
	s_movk_i32 s0, 0x80
	s_waitcnt lgkmcnt(0)
	v_mfma_f32_16x16x32_bf16 v[0:3], v[4:7], v[14:17], v[0:3]
	s_nop 7
	ds_write_b32 v8, v0 offset:55616
	ds_write_b32 v8, v1 offset:56132
	ds_write_b32 v8, v2 offset:56648
	ds_write_b32 v8, v3 offset:57164
	s_waitcnt lgkmcnt(0)
	s_barrier
	s_nop 0
	v_and_b32_e32 v0, 15, v247
	v_bfe_u32 v1, v247, 4, 2
	v_lshrrev_b32_e32 v2, 6, v247
	v_mul_u32_u24_e32 v3, 4416, v1
	v_add_u32_e32 v3, 0x15900, v3
	v_mul_u32_u24_e32 v4, 2064, v1
	v_lshl_add_u32 v11, v2, 4, v0
	v_lshl_add_u32 v4, v11, 2, v4
	v_add_u32_e32 v4, 0xd800, v4
	v_mul_u32_u24_e32 v5, 272, v0
	v_lshl_add_u32 v5, v1, 4, v5
	v_add_u32_e32 v5, 0x15900, v5
	ds_read_b32 v64, v4 offset:0
	ds_read_b32 v65, v4 offset:516
	ds_read_b32 v66, v4 offset:1032
	ds_read_b32 v67, v4 offset:1548
	ds_read_b32 v68, v4 offset:8256
	ds_read_b32 v69, v4 offset:8772
	ds_read_b32 v70, v4 offset:9288
	ds_read_b32 v71, v4 offset:9804
	ds_read_b32 v72, v4 offset:16512
	ds_read_b32 v73, v4 offset:17028
	ds_read_b32 v74, v4 offset:17544
	ds_read_b32 v75, v4 offset:18060
	ds_read_b32 v76, v4 offset:24768
	ds_read_b32 v77, v4 offset:25284
	ds_read_b32 v78, v4 offset:25800
	ds_read_b32 v79, v4 offset:26316
	ds_read_b128 v[96:99], v5 offset:4352
	ds_read_b128 v[100:103], v5 offset:8704
	ds_read_b128 v[104:107], v5 offset:8768
	ds_read_b128 v[108:111], v5 offset:13056
	ds_read_b128 v[112:115], v5 offset:13120
	ds_read_b128 v[116:119], v5 offset:13184
	v_cmp_eq_u32_e32 vcc, 0, v0
	s_nop 1
	v_cndmask_b32_e64 v16, 0, 1.0, vcc
	v_cmp_eq_u32_e32 vcc, 1, v0
	s_nop 1
	v_cndmask_b32_e64 v17, 0, 1.0, vcc
	v_cmp_eq_u32_e32 vcc, 2, v0
	s_nop 1
	v_cndmask_b32_e64 v18, 0, 1.0, vcc
	v_cmp_eq_u32_e32 vcc, 3, v0
	s_nop 1
	v_cndmask_b32_e64 v19, 0, 1.0, vcc
	v_cmp_eq_u32_e32 vcc, 4, v0
	s_nop 1
	v_cndmask_b32_e64 v20, 0, 1.0, vcc
	v_cmp_eq_u32_e32 vcc, 5, v0
	s_nop 1
	v_cndmask_b32_e64 v21, 0, 1.0, vcc
	v_cmp_eq_u32_e32 vcc, 6, v0
	s_nop 1
	v_cndmask_b32_e64 v22, 0, 1.0, vcc
	v_cmp_eq_u32_e32 vcc, 7, v0
	s_nop 1
	v_cndmask_b32_e64 v23, 0, 1.0, vcc
	v_cmp_eq_u32_e32 vcc, 8, v0
	s_nop 1
	v_cndmask_b32_e64 v24, 0, 1.0, vcc
	v_cmp_eq_u32_e32 vcc, 9, v0
	s_nop 1
	v_cndmask_b32_e64 v25, 0, 1.0, vcc
	v_cmp_eq_u32_e32 vcc, 10, v0
	s_nop 1
	v_cndmask_b32_e64 v26, 0, 1.0, vcc
	v_cmp_eq_u32_e32 vcc, 11, v0
	s_nop 1
	v_cndmask_b32_e64 v27, 0, 1.0, vcc
	v_cmp_eq_u32_e32 vcc, 12, v0
	s_nop 1
	v_cndmask_b32_e64 v28, 0, 1.0, vcc
	v_cmp_eq_u32_e32 vcc, 13, v0
	s_nop 1
	v_cndmask_b32_e64 v29, 0, 1.0, vcc
	v_cmp_eq_u32_e32 vcc, 14, v0
	s_nop 1
	v_cndmask_b32_e64 v30, 0, 1.0, vcc
	v_cmp_eq_u32_e32 vcc, 15, v0
	s_nop 1
	v_cndmask_b32_e64 v31, 0, 1.0, vcc
	ds_read_b128 v[48:51], v3 offset:272
	ds_read_b128 v[32:35], v3 offset:544
	s_waitcnt lgkmcnt(1)
	v_fmac_f32_e32 v17, v48, v16
	ds_read_b128 v[48:51], v3 offset:816
	s_waitcnt lgkmcnt(1)
	v_fmac_f32_e32 v18, v32, v16
	v_fmac_f32_e32 v18, v33, v17
	ds_read_b128 v[32:35], v3 offset:1088
	s_waitcnt lgkmcnt(1)
	v_fmac_f32_e32 v19, v48, v16
	v_fmac_f32_e32 v19, v49, v17
	v_fmac_f32_e32 v19, v50, v18
	ds_read_b128 v[48:51], v3 offset:1360
	ds_read_b128 v[52:55], v3 offset:1376
	s_waitcnt lgkmcnt(2)
	v_fmac_f32_e32 v20, v32, v16
	v_fmac_f32_e32 v20, v33, v17
	v_fmac_f32_e32 v20, v34, v18
	v_fmac_f32_e32 v20, v35, v19
	ds_read_b128 v[32:35], v3 offset:1632
	ds_read_b128 v[36:39], v3 offset:1648
	s_waitcnt lgkmcnt(2)
	v_fmac_f32_e32 v21, v48, v16
	v_fmac_f32_e32 v21, v49, v17
	v_fmac_f32_e32 v21, v50, v18
	v_fmac_f32_e32 v21, v51, v19
	v_fmac_f32_e32 v21, v52, v20
	ds_read_b128 v[48:51], v3 offset:1904
	ds_read_b128 v[52:55], v3 offset:1920
	s_waitcnt lgkmcnt(2)
; #define LAS __attribute__((address_space(3)))
; __device__ __forceinline__ unsigned cvt_pk_bf16(float lo, float hi) { const bf16x2_t r = __builtin_convertvector((f32x2){lo, hi}, bf16x2_t); return __builtin_bit_cast(unsigned, r); }
; __device__ __forceinline__ bf16_t f2bf(float x) { return (bf16_t)(cvt_pk_bf16(x, 0.f) & 0xffffu); }
; __device__ __forceinline__ void rw_phaseA(LAS unsigned char* lds, const RwCtx& X, int item) {
;     ...
;     if (tid_s < 128) {
;         float x[64];
;         int zv = 0; asm volatile("" : "+v"(zv));
;         const LAS float* LABv = LAB + zv;
; #pragma unroll
;         for (int i = 0; i < 64; ++i) x[i] = XS[i * 129 + tid_s];
; #pragma unroll
;         for (int tt = 1; tt < 64; ++tt) { float a = x[tt];
; #pragma unroll
;             for (int s4 = 0; s4 < (tt + 3) / 4; ++s4) { const f32x4 l4 = *(const LAS f32x4*)(LABv + tt * 68 + s4 * 4);
;                 a += l4[0] * x[s4 * 4]; if (s4 * 4 + 1 < tt) a += l4[1] * x[s4 * 4 + 1]; if (s4 * 4 + 2 < tt) a += l4[2] * x[s4 * 4 + 2]; if (s4 * 4 + 3 < tt) a += l4[3] * x[s4 * 4 + 3]; }
;             x[tt] = a;
;     ...
;             __builtin_amdgcn_sched_barrier(0);
;     ...
;         }
;         LAS bf16_t* rowT = (tid_s < 64) ? (WT + tid_s * 72) : (UT + (tid_s - 64) * 72);
;         LAS bf16_t* colN = (tid_s < 64) ? (Wt + tid_s) : (Ut + (tid_s - 64));
; #pragma unroll
;         for (int g = 0; g < 8; ++g) { u32x4 o; o.x = cvt_pk_bf16(x[8 * g], x[8 * g + 1]); o.y = cvt_pk_bf16(x[8 * g + 2], x[8 * g + 3]); o.z = cvt_pk_bf16(x[8 * g + 4], x[8 * g + 5]); o.w = cvt_pk_bf16(x[8 * g + 6], x[8 * g + 7]);
;             *(LAS u32x4*)(rowT + 8 * g) = o; }
; #pragma unroll
;         for (int i = 0; i < 64; ++i) colN[i * 64] = f2bf(x[i]);
	v_fmac_f32_e32 v22, v32, v16
	v_fmac_f32_e32 v22, v33, v17
	v_fmac_f32_e32 v22, v34, v18
	v_fmac_f32_e32 v22, v35, v19
	v_fmac_f32_e32 v22, v36, v20
	v_fmac_f32_e32 v22, v37, v21
	ds_read_b128 v[32:35], v3 offset:2176
	ds_read_b128 v[36:39], v3 offset:2192
	s_waitcnt lgkmcnt(2)
	v_fmac_f32_e32 v23, v48, v16
	v_fmac_f32_e32 v23, v49, v17
	v_fmac_f32_e32 v23, v50, v18
	v_fmac_f32_e32 v23, v51, v19
	v_fmac_f32_e32 v23, v52, v20
	v_fmac_f32_e32 v23, v53, v21
	v_fmac_f32_e32 v23, v54, v22
	ds_read_b128 v[48:51], v3 offset:2448
	ds_read_b128 v[52:55], v3 offset:2464
	ds_read_b128 v[56:59], v3 offset:2480
	s_waitcnt lgkmcnt(3)
	v_fmac_f32_e32 v24, v32, v16
	v_fmac_f32_e32 v24, v33, v17
	v_fmac_f32_e32 v24, v34, v18
	v_fmac_f32_e32 v24, v35, v19
	v_fmac_f32_e32 v24, v36, v20
	v_fmac_f32_e32 v24, v37, v21
	v_fmac_f32_e32 v24, v38, v22
	v_fmac_f32_e32 v24, v39, v23
	ds_read_b128 v[32:35], v3 offset:2720
	ds_read_b128 v[36:39], v3 offset:2736
	ds_read_b128 v[40:43], v3 offset:2752
	s_waitcnt lgkmcnt(3)
	v_fmac_f32_e32 v25, v48, v16
	v_fmac_f32_e32 v25, v49, v17
	v_fmac_f32_e32 v25, v50, v18
	v_fmac_f32_e32 v25, v51, v19
	v_fmac_f32_e32 v25, v52, v20
	v_fmac_f32_e32 v25, v53, v21
	v_fmac_f32_e32 v25, v54, v22
	v_fmac_f32_e32 v25, v55, v23
	v_fmac_f32_e32 v25, v56, v24
	ds_read_b128 v[48:51], v3 offset:2992
	ds_read_b128 v[52:55], v3 offset:3008
	ds_read_b128 v[56:59], v3 offset:3024
	s_waitcnt lgkmcnt(3)
	v_fmac_f32_e32 v26, v32, v16
	v_fmac_f32_e32 v26, v33, v17
	v_fmac_f32_e32 v26, v34, v18
	v_fmac_f32_e32 v26, v35, v19
	v_fmac_f32_e32 v26, v36, v20
	v_fmac_f32_e32 v26, v37, v21
	v_fmac_f32_e32 v26, v38, v22
	v_fmac_f32_e32 v26, v39, v23
	v_fmac_f32_e32 v26, v40, v24
	v_fmac_f32_e32 v26, v41, v25
	ds_read_b128 v[32:35], v3 offset:3264
	ds_read_b128 v[36:39], v3 offset:3280
	ds_read_b128 v[40:43], v3 offset:3296
	s_waitcnt lgkmcnt(3)
	v_fmac_f32_e32 v27, v48, v16
	v_fmac_f32_e32 v27, v49, v17
	v_fmac_f32_e32 v27, v50, v18
	v_fmac_f32_e32 v27, v51, v19
	v_fmac_f32_e32 v27, v52, v20
	v_fmac_f32_e32 v27, v53, v21
	v_fmac_f32_e32 v27, v54, v22
	v_fmac_f32_e32 v27, v55, v23
	v_fmac_f32_e32 v27, v56, v24
	v_fmac_f32_e32 v27, v57, v25
	v_fmac_f32_e32 v27, v58, v26
	ds_read_b128 v[48:51], v3 offset:3536
	ds_read_b128 v[52:55], v3 offset:3552
	ds_read_b128 v[56:59], v3 offset:3568
	ds_read_b128 v[60:63], v3 offset:3584
	s_waitcnt lgkmcnt(4)
	v_fmac_f32_e32 v28, v32, v16
	v_fmac_f32_e32 v28, v33, v17
	v_fmac_f32_e32 v28, v34, v18
	v_fmac_f32_e32 v28, v35, v19
	v_fmac_f32_e32 v28, v36, v20
	v_fmac_f32_e32 v28, v37, v21
	v_fmac_f32_e32 v28, v38, v22
	v_fmac_f32_e32 v28, v39, v23
	v_fmac_f32_e32 v28, v40, v24
	v_fmac_f32_e32 v28, v41, v25
	v_fmac_f32_e32 v28, v42, v26
	v_fmac_f32_e32 v28, v43, v27
	ds_read_b128 v[32:35], v3 offset:3808
	ds_read_b128 v[36:39], v3 offset:3824
	ds_read_b128 v[40:43], v3 offset:3840
	ds_read_b128 v[44:47], v3 offset:3856
	s_waitcnt lgkmcnt(4)
	v_fmac_f32_e32 v29, v48, v16
	v_fmac_f32_e32 v29, v49, v17
	v_fmac_f32_e32 v29, v50, v18
	v_fmac_f32_e32 v29, v51, v19
	v_fmac_f32_e32 v29, v52, v20
	v_fmac_f32_e32 v29, v53, v21
	v_fmac_f32_e32 v29, v54, v22
	v_fmac_f32_e32 v29, v55, v23
	v_fmac_f32_e32 v29, v56, v24
	v_fmac_f32_e32 v29, v57, v25
	v_fmac_f32_e32 v29, v58, v26
	v_fmac_f32_e32 v29, v59, v27
	v_fmac_f32_e32 v29, v60, v28
	ds_read_b128 v[48:51], v3 offset:4080
	ds_read_b128 v[52:55], v3 offset:4096
	ds_read_b128 v[56:59], v3 offset:4112
	ds_read_b128 v[60:63], v3 offset:4128
	s_waitcnt lgkmcnt(4)
	v_fmac_f32_e32 v30, v32, v16
	v_fmac_f32_e32 v30, v33, v17
	v_fmac_f32_e32 v30, v34, v18
	v_fmac_f32_e32 v30, v35, v19
	v_fmac_f32_e32 v30, v36, v20
	v_fmac_f32_e32 v30, v37, v21
	v_fmac_f32_e32 v30, v38, v22
	v_fmac_f32_e32 v30, v39, v23
	v_fmac_f32_e32 v30, v40, v24
	v_fmac_f32_e32 v30, v41, v25
	v_fmac_f32_e32 v30, v42, v26
	v_fmac_f32_e32 v30, v43, v27
	v_fmac_f32_e32 v30, v44, v28
	v_fmac_f32_e32 v30, v45, v29
	s_waitcnt lgkmcnt(0)
	v_fmac_f32_e32 v31, v48, v16
	v_fmac_f32_e32 v31, v49, v17
	v_fmac_f32_e32 v31, v50, v18
	v_fmac_f32_e32 v31, v51, v19
	v_fmac_f32_e32 v31, v52, v20
	v_fmac_f32_e32 v31, v53, v21
	v_fmac_f32_e32 v31, v54, v22
	v_fmac_f32_e32 v31, v55, v23
	v_fmac_f32_e32 v31, v56, v24
	v_fmac_f32_e32 v31, v57, v25
	v_fmac_f32_e32 v31, v58, v26
	v_fmac_f32_e32 v31, v59, v27
	v_fmac_f32_e32 v31, v60, v28
	v_fmac_f32_e32 v31, v61, v29
	v_fmac_f32_e32 v31, v62, v30
	v_lshlrev_b32_e32 v6, 10, v1
	v_lshl_add_u32 v6, v0, 2, v6
	v_add_u32_e32 v6, 0x1d000, v6
	ds_write_b32 v6, v16 offset:0
	ds_write_b32 v6, v17 offset:64
	ds_write_b32 v6, v18 offset:128
	ds_write_b32 v6, v19 offset:192
	ds_write_b32 v6, v20 offset:256
	ds_write_b32 v6, v21 offset:320
	ds_write_b32 v6, v22 offset:384
	ds_write_b32 v6, v23 offset:448
	ds_write_b32 v6, v24 offset:512
	ds_write_b32 v6, v25 offset:576
	ds_write_b32 v6, v26 offset:640
	ds_write_b32 v6, v27 offset:704
	ds_write_b32 v6, v28 offset:768
	ds_write_b32 v6, v29 offset:832
	ds_write_b32 v6, v30 offset:896
	ds_write_b32 v6, v31 offset:960
	v_lshlrev_b32_e32 v7, 6, v0
	v_lshl_add_u32 v7, v1, 4, v7
	v_add_u32_e32 v7, 0x1d000, v7
	s_waitcnt lgkmcnt(0)
; #define LAS __attribute__((address_space(3)))
; __device__ __forceinline__ unsigned cvt_pk_bf16(float lo, float hi) { const bf16x2_t r = __builtin_convertvector((f32x2){lo, hi}, bf16x2_t); return __builtin_bit_cast(unsigned, r); }
; __device__ __forceinline__ bf16_t f2bf(float x) { return (bf16_t)(cvt_pk_bf16(x, 0.f) & 0xffffu); }
; __device__ __forceinline__ void rw_phaseA(LAS unsigned char* lds, const RwCtx& X, int item) {
;     ...
;     if (tid_s < 128) {
;         float x[64];
;         int zv = 0; asm volatile("" : "+v"(zv));
;         const LAS float* LABv = LAB + zv;
; #pragma unroll
;         for (int i = 0; i < 64; ++i) x[i] = XS[i * 129 + tid_s];
; #pragma unroll
;         for (int tt = 1; tt < 64; ++tt) { float a = x[tt];
; #pragma unroll
;             for (int s4 = 0; s4 < (tt + 3) / 4; ++s4) { const f32x4 l4 = *(const LAS f32x4*)(LABv + tt * 68 + s4 * 4);
;                 a += l4[0] * x[s4 * 4]; if (s4 * 4 + 1 < tt) a += l4[1] * x[s4 * 4 + 1]; if (s4 * 4 + 2 < tt) a += l4[2] * x[s4 * 4 + 2]; if (s4 * 4 + 3 < tt) a += l4[3] * x[s4 * 4 + 3]; }
;             x[tt] = a;
;     ...
;             __builtin_amdgcn_sched_barrier(0);
;     ...
;         }
;         LAS bf16_t* rowT = (tid_s < 64) ? (WT + tid_s * 72) : (UT + (tid_s - 64) * 72);
;         LAS bf16_t* colN = (tid_s < 64) ? (Wt + tid_s) : (Ut + (tid_s - 64));
; #pragma unroll
;         for (int g = 0; g < 8; ++g) { u32x4 o; o.x = cvt_pk_bf16(x[8 * g], x[8 * g + 1]); o.y = cvt_pk_bf16(x[8 * g + 2], x[8 * g + 3]); o.z = cvt_pk_bf16(x[8 * g + 4], x[8 * g + 5]); o.w = cvt_pk_bf16(x[8 * g + 6], x[8 * g + 7]);
;             *(LAS u32x4*)(rowT + 8 * g) = o; }
; #pragma unroll
;         for (int i = 0; i < 64; ++i) colN[i * 64] = f2bf(x[i]);
	ds_read_b128 v[80:83], v7 offset:0
	ds_read_b128 v[84:87], v7 offset:1024
	ds_read_b128 v[88:91], v7 offset:2048
	ds_read_b128 v[92:95], v7 offset:3072
	v_cmp_gt_u32_e32 vcc, 4, v2
	v_mul_u32_u24_e32 v8, 0x90, v11
	v_mov_b32_e32 v12, 0x17900
	v_mov_b32_e32 v13, 0x4800
	v_cndmask_b32_e32 v12, v12, v13, vcc
	v_add_u32_e32 v8, v8, v12
	v_lshl_add_u32 v8, v1, 3, v8
	v_lshlrev_b32_e32 v10, 1, v11
	v_mov_b32_e32 v12, 0x1f80
	v_mov_b32_e32 v13, 0
	v_cndmask_b32_e32 v12, v12, v13, vcc
	v_add_u32_e32 v10, v10, v12
	v_lshl_add_u32 v10, v1, 9, v10
	s_waitcnt lgkmcnt(0)
	v_mfma_f32_16x16x4_f32 v[120:123], v80, v64, 0
	v_mfma_f32_16x16x4_f32 v[120:123], v81, v65, v[120:123]
	v_mfma_f32_16x16x4_f32 v[120:123], v82, v66, v[120:123]
	v_mfma_f32_16x16x4_f32 v[120:123], v83, v67, v[120:123]
	s_nop 7
	s_nop 3
	v_mfma_f32_16x16x4_f32 v[68:71], v96, v120, v[68:71]
	v_mfma_f32_16x16x4_f32 v[68:71], v97, v121, v[68:71]
	v_mfma_f32_16x16x4_f32 v[68:71], v98, v122, v[68:71]
	v_mfma_f32_16x16x4_f32 v[68:71], v99, v123, v[68:71]
	v_mfma_f32_16x16x4_f32 v[72:75], v100, v120, v[72:75]
	v_mfma_f32_16x16x4_f32 v[72:75], v101, v121, v[72:75]
	v_mfma_f32_16x16x4_f32 v[72:75], v102, v122, v[72:75]
	v_mfma_f32_16x16x4_f32 v[72:75], v103, v123, v[72:75]
	v_mfma_f32_16x16x4_f32 v[76:79], v108, v120, v[76:79]
	v_mfma_f32_16x16x4_f32 v[76:79], v109, v121, v[76:79]
	v_mfma_f32_16x16x4_f32 v[76:79], v110, v122, v[76:79]
	v_mfma_f32_16x16x4_f32 v[76:79], v111, v123, v[76:79]
	s_nop 7
	s_nop 3
	v_mfma_f32_16x16x4_f32 v[124:127], v84, v68, 0
	v_mfma_f32_16x16x4_f32 v[124:127], v85, v69, v[124:127]
	v_mfma_f32_16x16x4_f32 v[124:127], v86, v70, v[124:127]
	v_mfma_f32_16x16x4_f32 v[124:127], v87, v71, v[124:127]
	s_nop 7
	s_nop 3
	v_mfma_f32_16x16x4_f32 v[72:75], v104, v124, v[72:75]
	v_mfma_f32_16x16x4_f32 v[72:75], v105, v125, v[72:75]
	v_mfma_f32_16x16x4_f32 v[72:75], v106, v126, v[72:75]
	v_mfma_f32_16x16x4_f32 v[72:75], v107, v127, v[72:75]
	v_mfma_f32_16x16x4_f32 v[76:79], v112, v124, v[76:79]
	v_mfma_f32_16x16x4_f32 v[76:79], v113, v125, v[76:79]
	v_mfma_f32_16x16x4_f32 v[76:79], v114, v126, v[76:79]
	v_mfma_f32_16x16x4_f32 v[76:79], v115, v127, v[76:79]
	s_nop 7
	s_nop 3
	v_mfma_f32_16x16x4_f32 v[128:131], v88, v72, 0
	v_mfma_f32_16x16x4_f32 v[128:131], v89, v73, v[128:131]
	v_mfma_f32_16x16x4_f32 v[128:131], v90, v74, v[128:131]
	v_mfma_f32_16x16x4_f32 v[128:131], v91, v75, v[128:131]
	s_nop 7
	s_nop 3
	v_mfma_f32_16x16x4_f32 v[76:79], v116, v128, v[76:79]
	v_mfma_f32_16x16x4_f32 v[76:79], v117, v129, v[76:79]
	v_mfma_f32_16x16x4_f32 v[76:79], v118, v130, v[76:79]
	v_mfma_f32_16x16x4_f32 v[76:79], v119, v131, v[76:79]
	s_nop 7
	s_nop 3
	v_mfma_f32_16x16x4_f32 v[132:135], v92, v76, 0
	v_mfma_f32_16x16x4_f32 v[132:135], v93, v77, v[132:135]
	v_mfma_f32_16x16x4_f32 v[132:135], v94, v78, v[132:135]
	v_mfma_f32_16x16x4_f32 v[132:135], v95, v79, v[132:135]
	s_nop 7
	s_nop 3
	v_cvt_pk_bf16_f32 v148, v120, v121
	v_cvt_pk_bf16_f32 v149, v122, v123
	v_cvt_pk_bf16_f32 v150, v124, v125
	v_cvt_pk_bf16_f32 v151, v126, v127
	v_cvt_pk_bf16_f32 v152, v128, v129
	v_cvt_pk_bf16_f32 v153, v130, v131
	v_cvt_pk_bf16_f32 v154, v132, v133
	v_cvt_pk_bf16_f32 v155, v134, v135
	ds_write_b64 v8, v[148:149] offset:0
	ds_write_b16 v10, v148 offset:0
	ds_write_b16_d16_hi v10, v148 offset:128
	ds_write_b16 v10, v149 offset:256
	ds_write_b16_d16_hi v10, v149 offset:384
	ds_write_b64 v8, v[150:151] offset:32
	ds_write_b16 v10, v150 offset:2048
	ds_write_b16_d16_hi v10, v150 offset:2176
	ds_write_b16 v10, v151 offset:2304
	ds_write_b16_d16_hi v10, v151 offset:2432
	ds_write_b64 v8, v[152:153] offset:64
	ds_write_b16 v10, v152 offset:4096
	ds_write_b16_d16_hi v10, v152 offset:4224
	ds_write_b16 v10, v153 offset:4352
	ds_write_b16_d16_hi v10, v153 offset:4480
	ds_write_b64 v8, v[154:155] offset:96
	ds_write_b16 v10, v154 offset:6144
	ds_write_b16_d16_hi v10, v154 offset:6272
	ds_write_b16 v10, v155 offset:6400
	ds_write_b16_d16_hi v10, v155 offset:6528
	s_branch .LBB0_720
